# attention loops: row-sum chains start without the x+0 adds; P3 tile-skip mask kept scalar
# baseline (speedup 1.0000x reference)
.LBB0_552:
	s_andn2_b64 s[4:5], exec, s[38:39]
	s_andn2_b64 vcc, exec, s[38:39]
	s_cbranch_vccnz .LBB0_570
	s_add_i32 s49, s71, s48
	s_cmp_gt_i32 s49, s73
	s_cselect_b64 s[46:47], -1, 0
	s_cmp_lt_i32 s49, s74
	s_cselect_b64 s[78:79], -1, 0
	s_or_b64 s[46:47], s[46:47], s[78:79]
	s_and_b64 vcc, exec, s[46:47]
	s_cbranch_vccnz .LBB0_570
	s_add_i32 s46, s76, s72
	s_cmp_gt_i32 s46, 2
	s_cselect_b64 s[46:47], -1, 0
	s_and_b64 vcc, exec, s[46:47]
	s_cbranch_vccnz .LBB0_556
	ds_read2_b32 v[0:1], v191 offset0:59 offset1:58
	ds_read2_b32 v[2:3], v191 offset0:57 offset1:56
	ds_read2_b32 v[4:5], v191 offset0:51 offset1:50
	ds_read2_b32 v[6:7], v191 offset0:49 offset1:48
	ds_read2_b32 v[8:9], v191 offset0:43 offset1:42
	ds_read2_b32 v[10:11], v191 offset0:41 offset1:40
	ds_read2_b32 v[12:13], v191 offset0:35 offset1:34
	ds_read2_b32 v[14:15], v191 offset0:33 offset1:32
	s_waitcnt lgkmcnt(7)
	v_pk_add_f32 v[0:1], v[0:1], v[78:79] op_sel_hi:[1,0] neg_lo:[0,1] neg_hi:[0,1]
	ds_read2_b32 v[16:17], v191 offset0:27 offset1:26
	s_waitcnt lgkmcnt(7)
	v_pk_add_f32 v[2:3], v[2:3], v[78:79] op_sel_hi:[1,0] neg_lo:[0,1] neg_hi:[0,1]
	ds_read2_b32 v[18:19], v191 offset0:25 offset1:24
	s_waitcnt lgkmcnt(7)
	v_pk_add_f32 v[4:5], v[4:5], v[78:79] op_sel_hi:[1,0] neg_lo:[0,1] neg_hi:[0,1]
	ds_read2_b32 v[20:21], v191 offset0:19 offset1:18
	s_waitcnt lgkmcnt(7)
	v_pk_add_f32 v[6:7], v[6:7], v[78:79] op_sel_hi:[1,0] neg_lo:[0,1] neg_hi:[0,1]
	ds_read2_b32 v[22:23], v191 offset0:17 offset1:16
	s_waitcnt lgkmcnt(7)
	v_pk_add_f32 v[8:9], v[8:9], v[78:79] op_sel_hi:[1,0] neg_lo:[0,1] neg_hi:[0,1]
	ds_read2_b32 v[24:25], v191 offset0:11 offset1:10
	s_waitcnt lgkmcnt(7)
	v_pk_add_f32 v[10:11], v[10:11], v[78:79] op_sel_hi:[1,0] neg_lo:[0,1] neg_hi:[0,1]
	ds_read2_b32 v[26:27], v191 offset0:9 offset1:8
	s_waitcnt lgkmcnt(7)
	v_pk_add_f32 v[12:13], v[12:13], v[78:79] op_sel_hi:[1,0] neg_lo:[0,1] neg_hi:[0,1]
	ds_read2_b32 v[28:29], v191 offset0:3 offset1:2
	s_waitcnt lgkmcnt(7)
	v_pk_add_f32 v[14:15], v[14:15], v[78:79] op_sel_hi:[1,0] neg_lo:[0,1] neg_hi:[0,1]
	ds_read2_b32 v[30:31], v191 offset0:1
	s_waitcnt lgkmcnt(7)
	v_pk_add_f32 v[16:17], v[16:17], v[78:79] op_sel_hi:[1,0] neg_lo:[0,1] neg_hi:[0,1]
	s_waitcnt lgkmcnt(6)
	v_pk_add_f32 v[18:19], v[18:19], v[78:79] op_sel_hi:[1,0] neg_lo:[0,1] neg_hi:[0,1]
	s_waitcnt lgkmcnt(5)
	v_pk_add_f32 v[20:21], v[20:21], v[78:79] op_sel_hi:[1,0] neg_lo:[0,1] neg_hi:[0,1]
	s_waitcnt lgkmcnt(4)
	v_pk_add_f32 v[22:23], v[22:23], v[78:79] op_sel_hi:[1,0] neg_lo:[0,1] neg_hi:[0,1]
	s_waitcnt lgkmcnt(3)
	v_pk_add_f32 v[24:25], v[24:25], v[78:79] op_sel_hi:[1,0] neg_lo:[0,1] neg_hi:[0,1]
	s_waitcnt lgkmcnt(2)
	v_pk_add_f32 v[26:27], v[26:27], v[78:79] op_sel_hi:[1,0] neg_lo:[0,1] neg_hi:[0,1]
	s_waitcnt lgkmcnt(1)
	v_pk_add_f32 v[28:29], v[28:29], v[78:79] op_sel_hi:[1,0] neg_lo:[0,1] neg_hi:[0,1]
	s_waitcnt lgkmcnt(0)
	v_pk_add_f32 v[30:31], v[30:31], v[78:79] op_sel_hi:[1,0] neg_lo:[0,1] neg_hi:[0,1]

.LBB0_569:
	v_exp_f32_e32 v0, v48
	v_exp_f32_e32 v148, v49
	v_exp_f32_e32 v2, v50
	v_exp_f32_e32 v150, v51
	v_exp_f32_e32 v4, v52
	v_exp_f32_e32 v152, v53
	v_exp_f32_e32 v6, v54
	v_exp_f32_e32 v154, v55
	v_cvt_pk_bf16_f32 v48, v0, v148
	v_cvt_pk_bf16_f32 v49, v2, v150
	v_cvt_pk_bf16_f32 v50, v4, v152
	v_cvt_pk_bf16_f32 v51, v6, v154
	v_exp_f32_e32 v8, v56
	v_exp_f32_e32 v156, v57
	s_waitcnt lgkmcnt(0)
	v_mfma_f32_32x32x16_bf16 v[96:111], v[12:15], v[48:51], v[96:111]
	v_exp_f32_e32 v10, v58
	v_exp_f32_e32 v158, v59
	v_exp_f32_e32 v12, v60
	v_exp_f32_e32 v160, v61
	v_exp_f32_e32 v14, v62
	v_exp_f32_e32 v162, v63
	v_exp_f32_e32 v1, v32
	v_mfma_f32_32x32x16_bf16 v[80:95], v[144:147], v[48:51], v[80:95]
	v_exp_f32_e32 v149, v33
	v_exp_f32_e32 v3, v34
	v_exp_f32_e32 v151, v35
	v_cvt_pk_bf16_f32 v32, v8, v156
	v_cvt_pk_bf16_f32 v33, v10, v158
	v_cvt_pk_bf16_f32 v34, v12, v160
	v_cvt_pk_bf16_f32 v35, v14, v162
	v_exp_f32_e32 v5, v36
	v_exp_f32_e32 v153, v37
	v_mfma_f32_32x32x16_bf16 v[96:111], v[74:77], v[32:35], v[96:111]
	v_exp_f32_e32 v7, v38
	v_exp_f32_e32 v155, v39
	v_exp_f32_e32 v9, v40
	v_exp_f32_e32 v157, v41
	v_exp_f32_e32 v11, v42
	v_exp_f32_e32 v159, v43
	v_exp_f32_e32 v13, v44
	v_mfma_f32_32x32x16_bf16 v[80:95], v[70:73], v[32:35], v[80:95]
	v_cvt_pk_bf16_f32 v32, v1, v149
	v_cvt_pk_bf16_f32 v33, v3, v151
	v_cvt_pk_bf16_f32 v34, v5, v153
	v_cvt_pk_bf16_f32 v35, v7, v155
	v_exp_f32_e32 v161, v45
	v_exp_f32_e32 v15, v46
	v_exp_f32_e32 v163, v47
	v_mfma_f32_32x32x16_bf16 v[96:111], v[28:31], v[32:35], v[96:111]
	v_cvt_pk_bf16_f32 v30, v13, v161
	v_add_f32_e64 v28, v148, v0
	v_add_f32_e64 v29, v149, v1
	v_cvt_pk_bf16_f32 v31, v15, v163
	v_add_f32_e32 v28, v2, v28
	v_add_f32_e32 v29, v3, v29
	v_add_f32_e32 v36, v150, v28
	v_add_f32_e32 v37, v151, v29
	v_mfma_f32_32x32x16_bf16 v[80:95], v[24:27], v[32:35], v[80:95]
	v_add_f32_e64 v24, v4, v36
	v_add_f32_e64 v25, v5, v37
	v_cvt_pk_bf16_f32 v28, v9, v157
	v_add_f32_e64 v24, v152, v24
	v_add_f32_e64 v25, v153, v25
	v_cvt_pk_bf16_f32 v29, v11, v159
	v_add_f32_e32 v24, v6, v24
	v_add_f32_e32 v25, v7, v25
	v_add_f32_e32 v24, v154, v24
	v_add_f32_e32 v25, v155, v25
	v_mfma_f32_32x32x16_bf16 v[96:111], v[20:23], v[28:31], v[96:111]
	v_add_f32_e64 v24, v8, v24
	v_add_f32_e64 v25, v9, v25
	v_add_f32_e64 v24, v156, v24
	v_add_f32_e64 v25, v157, v25
	v_add_f32_e32 v20, v10, v24
	v_add_f32_e32 v21, v11, v25
	v_add_f32_e32 v20, v158, v20
	v_add_f32_e32 v21, v159, v21
	v_mfma_f32_32x32x16_bf16 v[80:95], v[16:19], v[28:31], v[80:95]
	v_add_f32_e64 v20, v12, v20
	v_add_f32_e64 v21, v13, v21
	v_add_f32_e64 v20, v160, v20
	v_add_f32_e64 v21, v161, v21
	v_add_f32_e32 v20, v14, v20
	v_add_f32_e32 v21, v15, v21
	v_add_f32_e32 v20, v162, v20
	v_add_f32_e32 v21, v163, v21
	v_add_f32_e32 v20, v20, v21
	v_add_f32_e32 v171, v171, v20
	s_mov_b64 s[44:45], 0
	s_andn2_b64 vcc, exec, s[42:43]
	s_cbranch_vccz .LBB0_571
	s_branch .LBB0_574

.LBB0_1349:
	v_exp_f32_e32 v174, v64
	v_exp_f32_e32 v176, v65
	v_exp_f32_e32 v182, v66
	v_exp_f32_e32 v184, v67
	v_exp_f32_e32 v68, v68
	v_exp_f32_e32 v186, v69
	v_exp_f32_e32 v70, v70
	v_exp_f32_e32 v188, v71
	v_cvt_pk_bf16_f32 v64, v174, v176
	v_cvt_pk_bf16_f32 v65, v182, v184
	v_cvt_pk_bf16_f32 v66, v68, v186
	v_cvt_pk_bf16_f32 v67, v70, v188
	v_exp_f32_e32 v72, v72
	v_exp_f32_e32 v190, v73
	s_waitcnt lgkmcnt(0)
	v_mfma_f32_32x32x16_bf16 v[32:47], v[140:143], v[64:67], v[32:47]
	v_exp_f32_e32 v74, v74
	v_exp_f32_e32 v192, v75
	v_exp_f32_e32 v76, v76
	v_exp_f32_e32 v140, v77
	v_exp_f32_e32 v78, v78
	v_exp_f32_e32 v142, v79
	v_exp_f32_e32 v175, v48
	v_mfma_f32_32x32x16_bf16 v[16:31], v[136:139], v[64:67], v[16:31]
	v_exp_f32_e32 v177, v49
	v_exp_f32_e32 v183, v50
	v_exp_f32_e32 v185, v51
	v_cvt_pk_bf16_f32 v48, v72, v190
	v_cvt_pk_bf16_f32 v49, v74, v192
	v_cvt_pk_bf16_f32 v50, v76, v140
	v_cvt_pk_bf16_f32 v51, v78, v142
	v_exp_f32_e32 v69, v52
	v_exp_f32_e32 v187, v53
	v_mfma_f32_32x32x16_bf16 v[32:47], v[132:135], v[48:51], v[32:47]
	v_exp_f32_e32 v71, v54
	v_exp_f32_e32 v189, v55
	v_exp_f32_e32 v73, v56
	v_add_f32_e32 v52, v176, v174
	v_add_f32_e32 v53, v177, v175
	v_exp_f32_e32 v191, v57
	v_add_f32_e32 v52, v182, v52
	v_add_f32_e32 v53, v183, v53
	v_mfma_f32_32x32x16_bf16 v[16:31], v[128:131], v[48:51], v[16:31]
	v_cvt_pk_bf16_f32 v48, v175, v177
	v_cvt_pk_bf16_f32 v49, v183, v185
	v_cvt_pk_bf16_f32 v50, v69, v187
	v_cvt_pk_bf16_f32 v51, v71, v189
	v_add_f32_e64 v56, v184, v52
	v_add_f32_e64 v57, v185, v53
	v_exp_f32_e32 v75, v58
	v_exp_f32_e32 v193, v59
	v_mfma_f32_32x32x16_bf16 v[32:47], v[124:127], v[48:51], v[32:47]
	v_exp_f32_e32 v77, v60
	v_exp_f32_e32 v141, v61
	v_exp_f32_e32 v79, v62
	v_exp_f32_e32 v143, v63
	v_cvt_pk_bf16_f32 v52, v73, v191
	v_cvt_pk_bf16_f32 v53, v75, v193
	v_cvt_pk_bf16_f32 v54, v77, v141
	v_mfma_f32_32x32x16_bf16 v[16:31], v[120:123], v[48:51], v[16:31]
	v_add_f32_e64 v48, v68, v56
	v_add_f32_e64 v49, v69, v57
	v_cvt_pk_bf16_f32 v55, v79, v143
	v_add_f32_e64 v48, v186, v48
	v_add_f32_e64 v49, v187, v49
	s_mov_b64 s[4:5], 0
	v_add_f32_e32 v48, v70, v48
	v_add_f32_e32 v49, v71, v49
	s_nop 0
	v_add_f32_e32 v48, v188, v48
	v_add_f32_e32 v49, v189, v49
	v_mfma_f32_32x32x16_bf16 v[32:47], v[116:119], v[52:55], v[32:47]
	v_add_f32_e64 v48, v72, v48
	v_add_f32_e64 v49, v73, v49
	v_add_f32_e64 v48, v190, v48
	v_add_f32_e64 v49, v191, v49
	v_add_f32_e64 v48, v74, v48
	v_add_f32_e64 v49, v75, v49
	v_add_f32_e32 v48, v192, v48
	v_add_f32_e32 v49, v193, v49
	v_mfma_f32_32x32x16_bf16 v[16:31], v[112:115], v[52:55], v[16:31]
	v_add_f32_e64 v48, v76, v48
	v_add_f32_e64 v49, v77, v49
	v_add_f32_e64 v48, v140, v48
	v_add_f32_e64 v49, v141, v49
	v_add_f32_e64 v48, v78, v48
	v_add_f32_e64 v49, v79, v49
	v_add_f32_e32 v48, v142, v48
	v_add_f32_e32 v49, v143, v49
	s_nop 0
	v_add_f32_e32 v48, v48, v49
	v_add_f32_e32 v164, v164, v48
